# v14 + P5 K loop LDS-DMA balance 2/6/2/6 -> 4/4/4/4 (two half-tile refills issued one super-phase later, waits re-derived 8/6/8/6)
# speedup vs baseline: 1.0062x; 1.0062x over previous
.LBB0_906:
	s_cmp_lt_i32 s26, 6
	s_cselect_b64 s[10:11], -1, 0
	s_and_b64 s[0:1], s[10:11], s[0:1]
	v_readlane_b32 s70, v249, 45
	s_andn2_b64 vcc, exec, s[0:1]
	v_readlane_b32 s71, v249, 46
	s_cbranch_vccnz .LBB0_928
	s_cmpk_gt_i32 s2, 0xb57
	v_mov_b32_e32 v12, v184
	s_movk_i32 s4, 0x400
	s_cbranch_scc1 .LBB0_928
	v_lshl_add_u32 v0, v12, 4, s31
	v_add_u32_e32 v1, 0x2000, v0
	v_ashrrev_i32_e32 v2, 31, v1
	v_lshrrev_b32_e32 v2, 22, v2
	v_add_u32_e32 v2, v1, v2
	v_ashrrev_i32_e32 v2, 10, v2
	v_mul_i32_i24_e32 v3, 0x400, v2
	v_sub_u32_e32 v1, v1, v3
	v_lshrrev_b32_e32 v3, 4, v1
	v_bitop3_b32 v1, v3, v1, 32 bitop3:0x6c
	v_ashrrev_i32_e32 v3, 31, v1
	v_lshrrev_b32_e32 v3, 26, v3
	v_add_u32_e32 v3, v1, v3
	v_lshlrev_b32_e32 v5, 3, v2
	v_lshlrev_b32_e32 v2, 5, v2
	v_and_b32_e32 v13, 32, v2
	v_and_b32_e32 v2, 0xffc0, v3
	v_sub_u32_e32 v1, v1, v2
	v_ashrrev_i32_e32 v4, 6, v3
	v_and_b32_e32 v5, -16, v5
	v_lshrrev_b16_e32 v2, 7, v1
	v_add_u32_e32 v5, v4, v5
	v_and_b32_e32 v2, 1, v2
	v_and_b32_e32 v4, 3, v4
	s_mov_b32 s0, 0x7fffffe0
	v_lshrrev_b32_e32 v6, 2, v5
	v_lshlrev_b32_e32 v7, 1, v5
	v_add_u16_e32 v1, v1, v2
	v_mov_b32_e32 v2, 1
	v_and_or_b32 v4, v5, s0, v4
	v_and_b32_e32 v6, 4, v6
	v_and_b32_e32 v7, 24, v7
	v_ashrrev_i16_sdwa v1, v2, sext(v1) dst_sel:DWORD dst_unused:UNUSED_PAD src0_sel:DWORD src1_sel:BYTE_0
	v_or3_b32 v4, v4, v6, v7
	v_bfe_i32 v14, v1, 0, 16
	v_mul_lo_u32 v4, v4, s4
	v_add_u32_e32 v1, v13, v14
	v_mul_lo_u32 v15, v5, s4
	v_add_lshl_u32 v128, v4, v1, 1
	v_add_lshl_u32 v130, v1, v15, 1
	v_ashrrev_i32_e32 v1, 31, v0
	v_lshrrev_b32_e32 v1, 22, v1
	v_add_u32_e32 v1, v0, v1
	v_ashrrev_i32_e32 v1, 10, v1
	v_mul_i32_i24_e32 v3, 0x400, v1
	v_sub_u32_e32 v0, v0, v3
	v_lshrrev_b32_e32 v3, 4, v0
	v_bitop3_b32 v0, v3, v0, 32 bitop3:0x6c
	v_ashrrev_i32_e32 v3, 31, v0
	v_lshrrev_b32_e32 v3, 26, v3
	v_add_u32_e32 v3, v0, v3
	v_lshlrev_b32_e32 v5, 3, v1
	v_ashrrev_i32_e32 v4, 6, v3
	v_and_b32_e32 v5, -16, v5
	v_add_u32_e32 v5, v4, v5
	v_and_b32_e32 v4, 3, v4
	s_ashr_i32 s5, s4, 31
	v_and_or_b32 v4, v5, s0, v4
	v_readlane_b32 s0, v248, 20
	s_lshl_b64 s[16:17], s[4:5], 8
	s_lshl_b64 s[18:19], s[4:5], 9
	v_readlane_b32 s1, v248, 21
	s_movk_i32 s3, 0x16c
	s_and_b64 s[0:1], s[0:1], exec
	s_cselect_b32 s0, s3, 0x16b
	v_readlane_b32 s1, v248, 22
	s_mul_i32 s0, s1, s0
	v_readlane_b32 s1, v248, 19
	s_add_i32 s0, s0, s1
	s_mul_hi_i32 s1, s0, 0x2e8ba2e9
	s_lshr_b32 s6, s1, 31
	s_ashr_i32 s1, s1, 5
	s_add_i32 s1, s1, s6
	v_lshlrev_b32_e32 v1, 5, v1
	s_lshl_b32 s7, s1, 3
	v_and_b32_e32 v16, 32, v1
	v_and_b32_e32 v1, 0xc0, v3
	s_sub_i32 s6, 0x84, s7
	v_sub_u32_e32 v0, v0, v1
	s_min_u32 s8, s6, 8
	s_mulk_i32 s1, 0xb0
	v_ashrrev_i16_sdwa v0, v2, sext(v0) dst_sel:DWORD dst_unused:UNUSED_PAD src0_sel:DWORD src1_sel:BYTE_0
	s_sub_i32 s9, s0, s1
	v_cvt_f32_ubyte0_e32 v2, s8
	v_lshrrev_b32_e32 v6, 2, v5
	v_lshlrev_b32_e32 v7, 1, v5
	v_cvt_f32_i32_e32 v1, s9
	v_rcp_iflag_f32_e32 v3, v2
	v_and_b32_e32 v6, 4, v6
	v_and_b32_e32 v7, 24, v7
	v_or3_b32 v4, v4, v6, v7
	v_bfe_i32 v17, v0, 0, 16
	v_mul_lo_u32 v4, v4, s4
	v_add_u32_e32 v0, v16, v17
	v_mul_lo_u32 v18, v5, s4
	v_add_lshl_u32 v132, v4, v0, 1
	v_add_lshl_u32 v134, v0, v18, 1
	v_mul_f32_e32 v0, v1, v3
	v_trunc_f32_e32 v0, v0
	v_fma_f32 v1, -v0, v2, v1
	v_cvt_i32_f32_e32 v0, v0
	s_ashr_i32 s0, s9, 30
	s_or_b32 s6, s0, 1
	v_cmp_ge_f32_e64 s[0:1], |v1|, v2
	s_and_b64 s[0:1], s[0:1], exec
	s_cselect_b32 s0, s6, 0
	v_readfirstlane_b32 s1, v0
	s_add_i32 s6, s1, s0
	s_mul_i32 s0, s6, s8
	s_sub_i32 s0, s9, s0
	s_sext_i32_i16 s0, s0
	s_add_i32 s59, s7, s0
	s_ashr_i32 s0, s59, 31
	s_mul_i32 s0, s18, s0
	s_mul_hi_u32 s1, s18, s59
	s_add_i32 s7, s1, s0
	s_lshr_b64 s[0:1], s[4:5], 23
	s_mul_i32 s1, s0, s59
	s_add_i32 s7, s7, s1
	s_bfe_i64 s[8:9], s[6:7], 0x100000
	s_mul_i32 s1, s18, s9
	s_mul_hi_u32 s9, s18, s8
	s_add_i32 s1, s9, s1
	s_mul_i32 s0, s0, s8
	s_add_i32 s1, s1, s0
	s_mul_i32 s0, s18, s8
	v_readlane_b32 s8, v249, 47
	v_readlane_b32 s9, v249, 48
	s_add_u32 s42, s8, s0
	s_addc_u32 s43, s9, s1
	s_add_i32 s28, s31, 0
	s_add_i32 m0, s28, 0x10000
	s_mul_i32 s33, s18, s59
	global_load_lds_dwordx4 v132, s[42:43]
	s_add_i32 m0, s28, 0x12000
	s_add_u32 s0, s42, s16
	global_load_lds_dwordx4 v128, s[42:43]
	s_addc_u32 s1, s43, s17
	s_add_i32 m0, s28, 0x14000
	v_mov_b32_e32 v133, 0
	global_load_lds_dwordx4 v132, s[0:1]
	s_add_i32 m0, s28, 0x16000
	s_add_u32 s40, s34, s33
	s_addc_u32 s41, s35, s7
	s_add_i32 s33, s28, 0x2000
	global_load_lds_dwordx4 v128, s[0:1]
	s_mov_b32 m0, s28
	s_add_u32 s8, s40, s16
	global_load_lds_dwordx4 v134, s[40:41]
	s_mov_b32 m0, s33
	s_addc_u32 s9, s41, s17
	s_add_i32 s44, s28, 0x4000
	global_load_lds_dwordx4 v130, s[40:41]
	s_mov_b32 m0, s44
	s_add_i32 s45, s28, 0x6000
	global_load_lds_dwordx4 v134, s[8:9]
	s_mov_b32 m0, s45
	v_mov_b32_e32 v129, v133
	global_load_lds_dwordx4 v130, s[8:9]
	v_readlane_b32 s8, v248, 26
	v_readlane_b32 s9, v248, 27
	v_mov_b32_e32 v135, v133
	v_mov_b32_e32 v131, v133
	v_cndmask_b32_e64 v10, 0, 1, s[8:9]
	s_mov_b32 s46, 0
	v_lshl_add_u64 v[8:9], s[42:43], 0, v[132:133]
	v_lshl_add_u64 v[4:5], s[42:43], 0, v[128:129]
	v_lshl_add_u64 v[2:3], s[0:1], 0, v[132:133]
	v_lshl_add_u64 v[0:1], s[0:1], 0, v[128:129]
	v_lshl_add_u64 v[6:7], s[40:41], 0, v[134:135]
	v_cmp_ne_u32_e64 s[0:1], 1, v10
	s_andn2_b64 vcc, exec, s[8:9]
	v_lshl_add_u64 v[10:11], s[40:41], 0, v[130:131]
	v_mov_b32_e32 v232, v6
	v_mov_b32_e32 v233, v7
	v_mov_b32_e32 v234, v10
	v_mov_b32_e32 v235, v11
	s_cbranch_vccnz .LBB0_910
	s_barrier

.LBB0_919:
	s_and_b64 vcc, exec, s[8:9]
	s_cbranch_vccnz .Lzx921
	s_add_u32 s40, s40, 0x80
	s_addc_u32 s41, s41, 0
	s_add_u32 s61, s42, 0x100
	s_addc_u32 s62, s43, 0
	s_mov_b32 s42, 0
	ds_read_b128 v[144:147], v153
	ds_read_b128 v[158:161], v153 offset:1024
	ds_read_b128 v[162:165], v153 offset:2048
	ds_read_b128 v[166:169], v153 offset:3072
	ds_read_b128 v[170:173], v154
	ds_read_b128 v[174:177], v154 offset:1024
	ds_read_b128 v[178:181], v154 offset:2048
	ds_read_b128 v[186:189], v154 offset:3072
	s_add_i32 s63, s42, 2
	s_add_u32 s64, s40, 0x80
	s_addc_u32 s43, s41, 0
	s_cmp_eq_u32 s50, s42
	s_cselect_b32 s42, s6, s64
	s_cselect_b32 s43, s7, s43
	s_cselect_b32 s65, s39, s62
	s_cselect_b32 s64, s38, s61
	v_lshl_add_u64 v[148:149], v[232:233], 0, s[36:37]
	s_mov_b32 m0, s47
	s_nop 0
	global_load_lds_dwordx4 v[148:149], off
	v_lshl_add_u64 v[148:149], v[234:235], 0, s[36:37]
	s_mov_b32 m0, s48
	s_nop 0
	global_load_lds_dwordx4 v[148:149], off
	s_mov_b32 m0, s53
	v_lshl_add_u64 v[148:149], s[40:41], 0, v[136:137]
	ds_read_b128 v[190:193], v155
	ds_read_b128 v[194:197], v155 offset:1024
	ds_read_b128 v[198:201], v155 offset:2048
	ds_read_b128 v[202:205], v155 offset:3072
	ds_read_b128 v[206:209], v155 offset:4096
	ds_read_b128 v[210:213], v155 offset:5120
	ds_read_b128 v[214:217], v155 offset:6144
	ds_read_b128 v[224:227], v155 offset:7168
	global_load_lds_dwordx4 v[148:149], off
	v_lshl_add_u64 v[148:149], s[40:41], 0, v[138:139]
	s_mov_b32 m0, s54
	s_nop 0
	global_load_lds_dwordx4 v[148:149], off
	s_waitcnt vmcnt(8)
	s_waitcnt lgkmcnt(0)
	s_barrier
	s_setprio 1
	s_waitcnt lgkmcnt(0)
	v_mfma_f32_16x16x32_bf16 v[120:123], v[144:147], v[190:193], 0
	v_mfma_f32_16x16x32_bf16 v[116:119], v[162:165], v[190:193], 0
	v_mfma_f32_16x16x32_bf16 v[108:111], v[144:147], v[198:201], 0
	v_mfma_f32_16x16x32_bf16 v[100:103], v[162:165], v[198:201], 0
	v_mfma_f32_16x16x32_bf16 v[92:95], v[144:147], v[206:209], 0
	v_mfma_f32_16x16x32_bf16 v[84:87], v[162:165], v[206:209], 0
	v_mfma_f32_16x16x32_bf16 v[76:79], v[144:147], v[214:217], 0
	v_mfma_f32_16x16x32_bf16 v[68:71], v[162:165], v[214:217], 0
	v_mfma_f32_16x16x32_bf16 v[120:123], v[158:161], v[194:197], v[120:123]
	v_mfma_f32_16x16x32_bf16 v[116:119], v[166:169], v[194:197], v[116:119]
	v_mfma_f32_16x16x32_bf16 v[108:111], v[158:161], v[202:205], v[108:111]
	v_mfma_f32_16x16x32_bf16 v[100:103], v[166:169], v[202:205], v[100:103]
	v_mfma_f32_16x16x32_bf16 v[92:95], v[158:161], v[210:213], v[92:95]
	v_mfma_f32_16x16x32_bf16 v[84:87], v[166:169], v[210:213], v[84:87]
	v_mfma_f32_16x16x32_bf16 v[76:79], v[158:161], v[224:227], v[76:79]
	v_mfma_f32_16x16x32_bf16 v[68:71], v[166:169], v[224:227], v[68:71]
	s_setprio 0
	s_setprio 1
	v_mfma_f32_16x16x32_bf16 v[124:127], v[170:173], v[190:193], 0
	v_mfma_f32_16x16x32_bf16 v[112:115], v[178:181], v[190:193], 0
	v_mfma_f32_16x16x32_bf16 v[104:107], v[170:173], v[198:201], 0
	v_mfma_f32_16x16x32_bf16 v[96:99], v[178:181], v[198:201], 0
	v_mfma_f32_16x16x32_bf16 v[88:91], v[170:173], v[206:209], 0
	v_mfma_f32_16x16x32_bf16 v[80:83], v[178:181], v[206:209], 0
	v_mfma_f32_16x16x32_bf16 v[72:75], v[170:173], v[214:217], 0
	v_mfma_f32_16x16x32_bf16 v[64:67], v[178:181], v[214:217], 0
	v_mfma_f32_16x16x32_bf16 v[124:127], v[174:177], v[194:197], v[124:127]
	v_mfma_f32_16x16x32_bf16 v[112:115], v[186:189], v[194:197], v[112:115]
	v_mfma_f32_16x16x32_bf16 v[104:107], v[174:177], v[202:205], v[104:107]
	v_mfma_f32_16x16x32_bf16 v[96:99], v[186:189], v[202:205], v[96:99]
	v_mfma_f32_16x16x32_bf16 v[88:91], v[174:177], v[210:213], v[88:91]
	v_mfma_f32_16x16x32_bf16 v[80:83], v[186:189], v[210:213], v[80:83]
	v_mfma_f32_16x16x32_bf16 v[72:75], v[174:177], v[224:227], v[72:75]
	v_mfma_f32_16x16x32_bf16 v[64:67], v[186:189], v[224:227], v[64:67]
	s_setprio 0
	s_barrier
	s_mov_b32 m0, s55
	v_lshl_add_u64 v[148:149], s[64:65], 0, v[132:133]
	v_lshl_add_u64 v[182:183], s[64:65], 0, v[128:129]
	s_add_u32 s64, s64, s16
	ds_read_b128 v[190:193], v155 offset:16384
	ds_read_b128 v[194:197], v155 offset:17408
	ds_read_b128 v[198:201], v155 offset:18432
	ds_read_b128 v[202:205], v155 offset:19456
	ds_read_b128 v[206:209], v155 offset:20480
	ds_read_b128 v[210:213], v155 offset:21504
	ds_read_b128 v[214:217], v155 offset:22528
	ds_read_b128 v[224:227], v155 offset:23552
	global_load_lds_dwordx4 v[148:149], off
	s_mov_b32 m0, s56
	s_addc_u32 s65, s65, s17
	s_add_i32 s66, s51, s31
	global_load_lds_dwordx4 v[182:183], off
	v_lshl_add_u64 v[228:229], s[64:65], 0, v[132:133]
	s_mov_b32 m0, s66
	v_lshl_add_u64 v[230:231], s[64:65], 0, v[128:129]
	global_load_lds_dwordx4 v[228:229], off
	s_add_i32 m0, s66, 0x2000
	v_lshl_add_u64 v[232:233], s[42:43], 0, v[134:135]
	global_load_lds_dwordx4 v[230:231], off
	v_lshl_add_u64 v[234:235], s[42:43], 0, v[130:131]
	s_waitcnt vmcnt(6)
	s_waitcnt lgkmcnt(0)
	s_barrier
	s_setprio 1
	s_waitcnt lgkmcnt(0)
	v_mfma_f32_16x16x32_bf16 v[60:63], v[144:147], v[190:193], 0
	v_mfma_f32_16x16x32_bf16 v[52:55], v[162:165], v[190:193], 0
	v_mfma_f32_16x16x32_bf16 v[44:47], v[144:147], v[198:201], 0
	v_mfma_f32_16x16x32_bf16 v[36:39], v[162:165], v[198:201], 0
	v_mfma_f32_16x16x32_bf16 v[28:31], v[144:147], v[206:209], 0
	v_mfma_f32_16x16x32_bf16 v[20:23], v[162:165], v[206:209], 0
	v_mfma_f32_16x16x32_bf16 v[12:15], v[144:147], v[214:217], 0
	v_mfma_f32_16x16x32_bf16 v[4:7], v[162:165], v[214:217], 0
	v_mfma_f32_16x16x32_bf16 v[60:63], v[158:161], v[194:197], v[60:63]
	v_mfma_f32_16x16x32_bf16 v[52:55], v[166:169], v[194:197], v[52:55]
	v_mfma_f32_16x16x32_bf16 v[44:47], v[158:161], v[202:205], v[44:47]
	v_mfma_f32_16x16x32_bf16 v[36:39], v[166:169], v[202:205], v[36:39]
	v_mfma_f32_16x16x32_bf16 v[28:31], v[158:161], v[210:213], v[28:31]
	v_mfma_f32_16x16x32_bf16 v[20:23], v[166:169], v[210:213], v[20:23]
	v_mfma_f32_16x16x32_bf16 v[12:15], v[158:161], v[224:227], v[12:15]
	v_mfma_f32_16x16x32_bf16 v[4:7], v[166:169], v[224:227], v[4:7]
	s_setprio 0
	s_setprio 1
	v_mfma_f32_16x16x32_bf16 v[56:59], v[170:173], v[190:193], 0
	v_mfma_f32_16x16x32_bf16 v[48:51], v[178:181], v[190:193], 0
	v_mfma_f32_16x16x32_bf16 v[40:43], v[170:173], v[198:201], 0
	v_mfma_f32_16x16x32_bf16 v[32:35], v[178:181], v[198:201], 0
	v_mfma_f32_16x16x32_bf16 v[24:27], v[170:173], v[206:209], 0
	v_mfma_f32_16x16x32_bf16 v[16:19], v[178:181], v[206:209], 0
	v_mfma_f32_16x16x32_bf16 v[8:11], v[170:173], v[214:217], 0
	v_mfma_f32_16x16x32_bf16 v[0:3], v[178:181], v[214:217], 0
	v_mfma_f32_16x16x32_bf16 v[56:59], v[174:177], v[194:197], v[56:59]
	v_mfma_f32_16x16x32_bf16 v[48:51], v[186:189], v[194:197], v[48:51]
	v_mfma_f32_16x16x32_bf16 v[40:43], v[174:177], v[202:205], v[40:43]
	v_mfma_f32_16x16x32_bf16 v[32:35], v[186:189], v[202:205], v[32:35]
	v_mfma_f32_16x16x32_bf16 v[24:27], v[174:177], v[210:213], v[24:27]
	v_mfma_f32_16x16x32_bf16 v[16:19], v[186:189], v[210:213], v[16:19]
	v_mfma_f32_16x16x32_bf16 v[8:11], v[174:177], v[224:227], v[8:11]
	v_mfma_f32_16x16x32_bf16 v[0:3], v[186:189], v[224:227], v[0:3]
	s_setprio 0
	s_barrier
	s_add_i32 s64, 0, 0x18000
	v_add_u32_e32 v157, s64, v151
	s_add_i32 s65, 0, 0x1c000
	ds_read_b128 v[144:147], v157
	ds_read_b128 v[158:161], v157 offset:1024
	ds_read_b128 v[162:165], v157 offset:2048
	ds_read_b128 v[166:169], v157 offset:3072
	v_add_u32_e32 v157, s65, v151
	ds_read_b128 v[170:173], v157
	ds_read_b128 v[174:177], v157 offset:1024
	ds_read_b128 v[178:181], v157 offset:2048
	ds_read_b128 v[186:189], v157 offset:3072
	s_add_u32 s42, s42, s16
	s_addc_u32 s43, s43, s17
	s_mov_b32 m0, s28
	s_nop 0
	global_load_lds_dwordx4 v[232:233], off
	s_mov_b32 m0, s33
	s_nop 0
	global_load_lds_dwordx4 v[234:235], off
	s_mov_b32 m0, s44
	v_lshl_add_u64 v[236:237], s[42:43], 0, v[134:135]
	ds_read_b128 v[190:193], v155 offset:32768
	ds_read_b128 v[194:197], v155 offset:33792
	ds_read_b128 v[198:201], v155 offset:34816
	ds_read_b128 v[202:205], v155 offset:35840
	ds_read_b128 v[206:209], v155 offset:36864
	ds_read_b128 v[210:213], v155 offset:37888
	ds_read_b128 v[214:217], v155 offset:38912
	ds_read_b128 v[224:227], v155 offset:39936
	global_load_lds_dwordx4 v[236:237], off
	v_lshl_add_u64 v[236:237], s[42:43], 0, v[130:131]
	s_mov_b32 m0, s45
	s_nop 0
	global_load_lds_dwordx4 v[236:237], off
	s_waitcnt vmcnt(8)
	s_waitcnt lgkmcnt(0)
	s_barrier
	s_setprio 1
	s_waitcnt lgkmcnt(0)
	v_mfma_f32_16x16x32_bf16 v[120:123], v[144:147], v[190:193], v[120:123]
	v_mfma_f32_16x16x32_bf16 v[116:119], v[162:165], v[190:193], v[116:119]
	v_mfma_f32_16x16x32_bf16 v[108:111], v[144:147], v[198:201], v[108:111]
	v_mfma_f32_16x16x32_bf16 v[100:103], v[162:165], v[198:201], v[100:103]
	v_mfma_f32_16x16x32_bf16 v[92:95], v[144:147], v[206:209], v[92:95]
	v_mfma_f32_16x16x32_bf16 v[84:87], v[162:165], v[206:209], v[84:87]
	v_mfma_f32_16x16x32_bf16 v[76:79], v[144:147], v[214:217], v[76:79]
	v_mfma_f32_16x16x32_bf16 v[68:71], v[162:165], v[214:217], v[68:71]
	v_mfma_f32_16x16x32_bf16 v[120:123], v[158:161], v[194:197], v[120:123]
	v_mfma_f32_16x16x32_bf16 v[116:119], v[166:169], v[194:197], v[116:119]
	v_mfma_f32_16x16x32_bf16 v[108:111], v[158:161], v[202:205], v[108:111]
	v_mfma_f32_16x16x32_bf16 v[100:103], v[166:169], v[202:205], v[100:103]
	v_mfma_f32_16x16x32_bf16 v[92:95], v[158:161], v[210:213], v[92:95]
	v_mfma_f32_16x16x32_bf16 v[84:87], v[166:169], v[210:213], v[84:87]
	v_mfma_f32_16x16x32_bf16 v[76:79], v[158:161], v[224:227], v[76:79]
	v_mfma_f32_16x16x32_bf16 v[68:71], v[166:169], v[224:227], v[68:71]
	s_setprio 0
	s_setprio 1
	v_mfma_f32_16x16x32_bf16 v[124:127], v[170:173], v[190:193], v[124:127]
	v_mfma_f32_16x16x32_bf16 v[112:115], v[178:181], v[190:193], v[112:115]
	v_mfma_f32_16x16x32_bf16 v[104:107], v[170:173], v[198:201], v[104:107]
	v_mfma_f32_16x16x32_bf16 v[96:99], v[178:181], v[198:201], v[96:99]
	v_mfma_f32_16x16x32_bf16 v[88:91], v[170:173], v[206:209], v[88:91]
	v_mfma_f32_16x16x32_bf16 v[80:83], v[178:181], v[206:209], v[80:83]
	v_mfma_f32_16x16x32_bf16 v[72:75], v[170:173], v[214:217], v[72:75]
	v_mfma_f32_16x16x32_bf16 v[64:67], v[178:181], v[214:217], v[64:67]
	v_mfma_f32_16x16x32_bf16 v[124:127], v[174:177], v[194:197], v[124:127]
	v_mfma_f32_16x16x32_bf16 v[112:115], v[186:189], v[194:197], v[112:115]
	v_mfma_f32_16x16x32_bf16 v[104:107], v[174:177], v[202:205], v[104:107]
	v_mfma_f32_16x16x32_bf16 v[96:99], v[186:189], v[202:205], v[96:99]
	v_mfma_f32_16x16x32_bf16 v[88:91], v[174:177], v[210:213], v[88:91]
	v_mfma_f32_16x16x32_bf16 v[80:83], v[186:189], v[210:213], v[80:83]
	v_mfma_f32_16x16x32_bf16 v[72:75], v[174:177], v[224:227], v[72:75]
	v_mfma_f32_16x16x32_bf16 v[64:67], v[186:189], v[224:227], v[64:67]
	s_setprio 0
	s_barrier
	s_add_i32 s42, s64, s31
	v_lshl_add_u64 v[148:149], v[148:149], 0, s[36:37]
	s_mov_b32 m0, s42
	ds_read_b128 v[190:193], v155 offset:49152
	ds_read_b128 v[194:197], v155 offset:50176
	ds_read_b128 v[198:201], v155 offset:51200
	ds_read_b128 v[202:205], v155 offset:52224
	ds_read_b128 v[206:209], v155 offset:53248
	ds_read_b128 v[210:213], v155 offset:54272
	ds_read_b128 v[214:217], v155 offset:55296
	ds_read_b128 v[224:227], v155 offset:56320
	global_load_lds_dwordx4 v[148:149], off
	v_lshl_add_u64 v[148:149], v[182:183], 0, s[36:37]
	s_add_i32 m0, s42, 0x2000
	s_add_i32 s42, s65, s31
	global_load_lds_dwordx4 v[148:149], off
	v_lshl_add_u64 v[148:149], v[228:229], 0, s[36:37]
	s_mov_b32 m0, s42
	s_nop 0
	global_load_lds_dwordx4 v[148:149], off
	v_lshl_add_u64 v[148:149], v[230:231], 0, s[36:37]
	s_add_i32 m0, s42, 0x2000
	s_nop 0
	global_load_lds_dwordx4 v[148:149], off
	s_waitcnt vmcnt(6)
	s_waitcnt lgkmcnt(0)
	s_barrier
	s_setprio 1
	s_waitcnt lgkmcnt(0)
	v_mfma_f32_16x16x32_bf16 v[60:63], v[144:147], v[190:193], v[60:63]
	v_mfma_f32_16x16x32_bf16 v[52:55], v[162:165], v[190:193], v[52:55]
	v_mfma_f32_16x16x32_bf16 v[44:47], v[144:147], v[198:201], v[44:47]
	v_mfma_f32_16x16x32_bf16 v[36:39], v[162:165], v[198:201], v[36:39]
	v_mfma_f32_16x16x32_bf16 v[28:31], v[144:147], v[206:209], v[28:31]
	v_mfma_f32_16x16x32_bf16 v[20:23], v[162:165], v[206:209], v[20:23]
	v_mfma_f32_16x16x32_bf16 v[12:15], v[144:147], v[214:217], v[12:15]
	v_mfma_f32_16x16x32_bf16 v[4:7], v[162:165], v[214:217], v[4:7]
	v_mfma_f32_16x16x32_bf16 v[60:63], v[158:161], v[194:197], v[60:63]
	v_mfma_f32_16x16x32_bf16 v[52:55], v[166:169], v[194:197], v[52:55]
	v_mfma_f32_16x16x32_bf16 v[44:47], v[158:161], v[202:205], v[44:47]
	v_mfma_f32_16x16x32_bf16 v[36:39], v[166:169], v[202:205], v[36:39]
	v_mfma_f32_16x16x32_bf16 v[28:31], v[158:161], v[210:213], v[28:31]
	v_mfma_f32_16x16x32_bf16 v[20:23], v[166:169], v[210:213], v[20:23]
	v_mfma_f32_16x16x32_bf16 v[12:15], v[158:161], v[224:227], v[12:15]
	v_mfma_f32_16x16x32_bf16 v[4:7], v[166:169], v[224:227], v[4:7]
	s_setprio 0
	s_setprio 1
	v_mfma_f32_16x16x32_bf16 v[56:59], v[170:173], v[190:193], v[56:59]
	v_mfma_f32_16x16x32_bf16 v[48:51], v[178:181], v[190:193], v[48:51]
	v_mfma_f32_16x16x32_bf16 v[40:43], v[170:173], v[198:201], v[40:43]
	v_mfma_f32_16x16x32_bf16 v[32:35], v[178:181], v[198:201], v[32:35]
	v_mfma_f32_16x16x32_bf16 v[24:27], v[170:173], v[206:209], v[24:27]
	v_mfma_f32_16x16x32_bf16 v[16:19], v[178:181], v[206:209], v[16:19]
	v_mfma_f32_16x16x32_bf16 v[8:11], v[170:173], v[214:217], v[8:11]
	v_mfma_f32_16x16x32_bf16 v[0:3], v[178:181], v[214:217], v[0:3]
	v_mfma_f32_16x16x32_bf16 v[56:59], v[174:177], v[194:197], v[56:59]
	v_mfma_f32_16x16x32_bf16 v[48:51], v[186:189], v[194:197], v[48:51]
	v_mfma_f32_16x16x32_bf16 v[40:43], v[174:177], v[202:205], v[40:43]
	v_mfma_f32_16x16x32_bf16 v[32:35], v[186:189], v[202:205], v[32:35]
	v_mfma_f32_16x16x32_bf16 v[24:27], v[174:177], v[210:213], v[24:27]
	v_mfma_f32_16x16x32_bf16 v[16:19], v[186:189], v[210:213], v[16:19]
	v_mfma_f32_16x16x32_bf16 v[8:11], v[174:177], v[224:227], v[8:11]
	v_mfma_f32_16x16x32_bf16 v[0:3], v[186:189], v[224:227], v[0:3]
	s_setprio 0
	s_barrier
	s_add_u32 s40, s40, 0x100
	s_addc_u32 s41, s41, 0
	s_add_u32 s61, s61, 0x100
	s_addc_u32 s62, s62, 0
	s_cmp_ge_i32 s63, s49
	s_mov_b32 s42, s63
	s_cbranch_scc1 .LBB0_922
.LBB0_921:
	ds_read_b128 v[144:147], v153
	ds_read_b128 v[158:161], v153 offset:1024
	ds_read_b128 v[162:165], v153 offset:2048
	ds_read_b128 v[166:169], v153 offset:3072
	ds_read_b128 v[170:173], v154
	ds_read_b128 v[174:177], v154 offset:1024
	ds_read_b128 v[178:181], v154 offset:2048
	ds_read_b128 v[186:189], v154 offset:3072
	s_add_i32 s63, s42, 2
	s_add_u32 s64, s40, 0x80
	s_addc_u32 s43, s41, 0
	s_cmp_eq_u32 s50, s42
	s_cselect_b32 s42, s6, s64
	s_cselect_b32 s43, s7, s43
	s_cselect_b32 s65, s39, s62
	s_cselect_b32 s64, s38, s61
	v_lshl_add_u64 v[148:149], v[232:233], 0, s[36:37]
	s_mov_b32 m0, s47
	s_nop 0
	global_load_lds_dwordx4 v[148:149], off
	v_lshl_add_u64 v[148:149], v[234:235], 0, s[36:37]
	s_mov_b32 m0, s48
	s_nop 0
	global_load_lds_dwordx4 v[148:149], off
	s_mov_b32 m0, s53
	v_lshl_add_u64 v[148:149], s[40:41], 0, v[136:137]
	ds_read_b128 v[190:193], v155
	ds_read_b128 v[194:197], v155 offset:1024
	ds_read_b128 v[198:201], v155 offset:2048
	ds_read_b128 v[202:205], v155 offset:3072
	ds_read_b128 v[206:209], v155 offset:4096
	ds_read_b128 v[210:213], v155 offset:5120
	ds_read_b128 v[214:217], v155 offset:6144
	ds_read_b128 v[224:227], v155 offset:7168
	global_load_lds_dwordx4 v[148:149], off
	v_lshl_add_u64 v[148:149], s[40:41], 0, v[138:139]
	s_mov_b32 m0, s54
	s_nop 0
	global_load_lds_dwordx4 v[148:149], off
	s_waitcnt vmcnt(8)
	s_waitcnt lgkmcnt(0)
	s_barrier
	s_setprio 1
	s_waitcnt lgkmcnt(0)
	v_mfma_f32_16x16x32_bf16 v[120:123], v[144:147], v[190:193], v[120:123]
	v_mfma_f32_16x16x32_bf16 v[116:119], v[162:165], v[190:193], v[116:119]
	v_mfma_f32_16x16x32_bf16 v[108:111], v[144:147], v[198:201], v[108:111]
	v_mfma_f32_16x16x32_bf16 v[100:103], v[162:165], v[198:201], v[100:103]
	v_mfma_f32_16x16x32_bf16 v[92:95], v[144:147], v[206:209], v[92:95]
	v_mfma_f32_16x16x32_bf16 v[84:87], v[162:165], v[206:209], v[84:87]
	v_mfma_f32_16x16x32_bf16 v[76:79], v[144:147], v[214:217], v[76:79]
	v_mfma_f32_16x16x32_bf16 v[68:71], v[162:165], v[214:217], v[68:71]
	v_mfma_f32_16x16x32_bf16 v[120:123], v[158:161], v[194:197], v[120:123]
	v_mfma_f32_16x16x32_bf16 v[116:119], v[166:169], v[194:197], v[116:119]
	v_mfma_f32_16x16x32_bf16 v[108:111], v[158:161], v[202:205], v[108:111]
	v_mfma_f32_16x16x32_bf16 v[100:103], v[166:169], v[202:205], v[100:103]
	v_mfma_f32_16x16x32_bf16 v[92:95], v[158:161], v[210:213], v[92:95]
	v_mfma_f32_16x16x32_bf16 v[84:87], v[166:169], v[210:213], v[84:87]
	v_mfma_f32_16x16x32_bf16 v[76:79], v[158:161], v[224:227], v[76:79]
	v_mfma_f32_16x16x32_bf16 v[68:71], v[166:169], v[224:227], v[68:71]
	s_setprio 0
	s_setprio 1
	v_mfma_f32_16x16x32_bf16 v[124:127], v[170:173], v[190:193], v[124:127]
	v_mfma_f32_16x16x32_bf16 v[112:115], v[178:181], v[190:193], v[112:115]
	v_mfma_f32_16x16x32_bf16 v[104:107], v[170:173], v[198:201], v[104:107]
	v_mfma_f32_16x16x32_bf16 v[96:99], v[178:181], v[198:201], v[96:99]
	v_mfma_f32_16x16x32_bf16 v[88:91], v[170:173], v[206:209], v[88:91]
	v_mfma_f32_16x16x32_bf16 v[80:83], v[178:181], v[206:209], v[80:83]
	v_mfma_f32_16x16x32_bf16 v[72:75], v[170:173], v[214:217], v[72:75]
	v_mfma_f32_16x16x32_bf16 v[64:67], v[178:181], v[214:217], v[64:67]
	v_mfma_f32_16x16x32_bf16 v[124:127], v[174:177], v[194:197], v[124:127]
	v_mfma_f32_16x16x32_bf16 v[112:115], v[186:189], v[194:197], v[112:115]
	v_mfma_f32_16x16x32_bf16 v[104:107], v[174:177], v[202:205], v[104:107]
	v_mfma_f32_16x16x32_bf16 v[96:99], v[186:189], v[202:205], v[96:99]
	v_mfma_f32_16x16x32_bf16 v[88:91], v[174:177], v[210:213], v[88:91]
	v_mfma_f32_16x16x32_bf16 v[80:83], v[186:189], v[210:213], v[80:83]
	v_mfma_f32_16x16x32_bf16 v[72:75], v[174:177], v[224:227], v[72:75]
	v_mfma_f32_16x16x32_bf16 v[64:67], v[186:189], v[224:227], v[64:67]
	s_setprio 0
	s_barrier
	s_mov_b32 m0, s55
	v_lshl_add_u64 v[148:149], s[64:65], 0, v[132:133]
	v_lshl_add_u64 v[182:183], s[64:65], 0, v[128:129]
	s_add_u32 s64, s64, s16
	ds_read_b128 v[190:193], v155 offset:16384
	ds_read_b128 v[194:197], v155 offset:17408
	ds_read_b128 v[198:201], v155 offset:18432
	ds_read_b128 v[202:205], v155 offset:19456
	ds_read_b128 v[206:209], v155 offset:20480
	ds_read_b128 v[210:213], v155 offset:21504
	ds_read_b128 v[214:217], v155 offset:22528
	ds_read_b128 v[224:227], v155 offset:23552
	global_load_lds_dwordx4 v[148:149], off
	s_mov_b32 m0, s56
	s_addc_u32 s65, s65, s17
	s_add_i32 s66, s51, s31
	global_load_lds_dwordx4 v[182:183], off
	v_lshl_add_u64 v[228:229], s[64:65], 0, v[132:133]
	s_mov_b32 m0, s66
	v_lshl_add_u64 v[230:231], s[64:65], 0, v[128:129]
	global_load_lds_dwordx4 v[228:229], off
	s_add_i32 m0, s66, 0x2000
	v_lshl_add_u64 v[232:233], s[42:43], 0, v[134:135]
	global_load_lds_dwordx4 v[230:231], off
	v_lshl_add_u64 v[234:235], s[42:43], 0, v[130:131]
	s_waitcnt vmcnt(6)
	s_waitcnt lgkmcnt(0)
	s_barrier
	s_setprio 1
	s_waitcnt lgkmcnt(0)
	v_mfma_f32_16x16x32_bf16 v[60:63], v[144:147], v[190:193], v[60:63]
	v_mfma_f32_16x16x32_bf16 v[52:55], v[162:165], v[190:193], v[52:55]
	v_mfma_f32_16x16x32_bf16 v[44:47], v[144:147], v[198:201], v[44:47]
	v_mfma_f32_16x16x32_bf16 v[36:39], v[162:165], v[198:201], v[36:39]
	v_mfma_f32_16x16x32_bf16 v[28:31], v[144:147], v[206:209], v[28:31]
	v_mfma_f32_16x16x32_bf16 v[20:23], v[162:165], v[206:209], v[20:23]
	v_mfma_f32_16x16x32_bf16 v[12:15], v[144:147], v[214:217], v[12:15]
	v_mfma_f32_16x16x32_bf16 v[4:7], v[162:165], v[214:217], v[4:7]
	v_mfma_f32_16x16x32_bf16 v[60:63], v[158:161], v[194:197], v[60:63]
	v_mfma_f32_16x16x32_bf16 v[52:55], v[166:169], v[194:197], v[52:55]
	v_mfma_f32_16x16x32_bf16 v[44:47], v[158:161], v[202:205], v[44:47]
	v_mfma_f32_16x16x32_bf16 v[36:39], v[166:169], v[202:205], v[36:39]
	v_mfma_f32_16x16x32_bf16 v[28:31], v[158:161], v[210:213], v[28:31]
	v_mfma_f32_16x16x32_bf16 v[20:23], v[166:169], v[210:213], v[20:23]
	v_mfma_f32_16x16x32_bf16 v[12:15], v[158:161], v[224:227], v[12:15]
	v_mfma_f32_16x16x32_bf16 v[4:7], v[166:169], v[224:227], v[4:7]
	s_setprio 0
	s_setprio 1
	v_mfma_f32_16x16x32_bf16 v[56:59], v[170:173], v[190:193], v[56:59]
	v_mfma_f32_16x16x32_bf16 v[48:51], v[178:181], v[190:193], v[48:51]
	v_mfma_f32_16x16x32_bf16 v[40:43], v[170:173], v[198:201], v[40:43]
	v_mfma_f32_16x16x32_bf16 v[32:35], v[178:181], v[198:201], v[32:35]
	v_mfma_f32_16x16x32_bf16 v[24:27], v[170:173], v[206:209], v[24:27]
	v_mfma_f32_16x16x32_bf16 v[16:19], v[178:181], v[206:209], v[16:19]
	v_mfma_f32_16x16x32_bf16 v[8:11], v[170:173], v[214:217], v[8:11]
	v_mfma_f32_16x16x32_bf16 v[0:3], v[178:181], v[214:217], v[0:3]
	v_mfma_f32_16x16x32_bf16 v[56:59], v[174:177], v[194:197], v[56:59]
	v_mfma_f32_16x16x32_bf16 v[48:51], v[186:189], v[194:197], v[48:51]
	v_mfma_f32_16x16x32_bf16 v[40:43], v[174:177], v[202:205], v[40:43]
	v_mfma_f32_16x16x32_bf16 v[32:35], v[186:189], v[202:205], v[32:35]
	v_mfma_f32_16x16x32_bf16 v[24:27], v[174:177], v[210:213], v[24:27]
	v_mfma_f32_16x16x32_bf16 v[16:19], v[186:189], v[210:213], v[16:19]
	v_mfma_f32_16x16x32_bf16 v[8:11], v[174:177], v[224:227], v[8:11]
	v_mfma_f32_16x16x32_bf16 v[0:3], v[186:189], v[224:227], v[0:3]
	s_setprio 0
	s_barrier
	s_add_i32 s64, 0, 0x18000
	v_add_u32_e32 v157, s64, v151
	s_add_i32 s65, 0, 0x1c000
	ds_read_b128 v[144:147], v157
	ds_read_b128 v[158:161], v157 offset:1024
	ds_read_b128 v[162:165], v157 offset:2048
	ds_read_b128 v[166:169], v157 offset:3072
	v_add_u32_e32 v157, s65, v151
	ds_read_b128 v[170:173], v157
	ds_read_b128 v[174:177], v157 offset:1024
	ds_read_b128 v[178:181], v157 offset:2048
	ds_read_b128 v[186:189], v157 offset:3072
	s_add_u32 s42, s42, s16
	s_addc_u32 s43, s43, s17
	s_mov_b32 m0, s28
	s_nop 0
	global_load_lds_dwordx4 v[232:233], off
	s_mov_b32 m0, s33
	s_nop 0
	global_load_lds_dwordx4 v[234:235], off
	s_mov_b32 m0, s44
	v_lshl_add_u64 v[236:237], s[42:43], 0, v[134:135]
	ds_read_b128 v[190:193], v155 offset:32768
	ds_read_b128 v[194:197], v155 offset:33792
	ds_read_b128 v[198:201], v155 offset:34816
	ds_read_b128 v[202:205], v155 offset:35840
	ds_read_b128 v[206:209], v155 offset:36864
	ds_read_b128 v[210:213], v155 offset:37888
	ds_read_b128 v[214:217], v155 offset:38912
	ds_read_b128 v[224:227], v155 offset:39936
	global_load_lds_dwordx4 v[236:237], off
	v_lshl_add_u64 v[236:237], s[42:43], 0, v[130:131]
	s_mov_b32 m0, s45
	s_nop 0
	global_load_lds_dwordx4 v[236:237], off
	s_waitcnt vmcnt(8)
	s_waitcnt lgkmcnt(0)
	s_barrier
	s_setprio 1
	s_waitcnt lgkmcnt(0)
	v_mfma_f32_16x16x32_bf16 v[120:123], v[144:147], v[190:193], v[120:123]
	v_mfma_f32_16x16x32_bf16 v[116:119], v[162:165], v[190:193], v[116:119]
	v_mfma_f32_16x16x32_bf16 v[108:111], v[144:147], v[198:201], v[108:111]
	v_mfma_f32_16x16x32_bf16 v[100:103], v[162:165], v[198:201], v[100:103]
	v_mfma_f32_16x16x32_bf16 v[92:95], v[144:147], v[206:209], v[92:95]
	v_mfma_f32_16x16x32_bf16 v[84:87], v[162:165], v[206:209], v[84:87]
	v_mfma_f32_16x16x32_bf16 v[76:79], v[144:147], v[214:217], v[76:79]
	v_mfma_f32_16x16x32_bf16 v[68:71], v[162:165], v[214:217], v[68:71]
	v_mfma_f32_16x16x32_bf16 v[120:123], v[158:161], v[194:197], v[120:123]
	v_mfma_f32_16x16x32_bf16 v[116:119], v[166:169], v[194:197], v[116:119]
	v_mfma_f32_16x16x32_bf16 v[108:111], v[158:161], v[202:205], v[108:111]
	v_mfma_f32_16x16x32_bf16 v[100:103], v[166:169], v[202:205], v[100:103]
	v_mfma_f32_16x16x32_bf16 v[92:95], v[158:161], v[210:213], v[92:95]
	v_mfma_f32_16x16x32_bf16 v[84:87], v[166:169], v[210:213], v[84:87]
	v_mfma_f32_16x16x32_bf16 v[76:79], v[158:161], v[224:227], v[76:79]
	v_mfma_f32_16x16x32_bf16 v[68:71], v[166:169], v[224:227], v[68:71]
	s_setprio 0
	s_setprio 1
	v_mfma_f32_16x16x32_bf16 v[124:127], v[170:173], v[190:193], v[124:127]
	v_mfma_f32_16x16x32_bf16 v[112:115], v[178:181], v[190:193], v[112:115]
	v_mfma_f32_16x16x32_bf16 v[104:107], v[170:173], v[198:201], v[104:107]
	v_mfma_f32_16x16x32_bf16 v[96:99], v[178:181], v[198:201], v[96:99]
	v_mfma_f32_16x16x32_bf16 v[88:91], v[170:173], v[206:209], v[88:91]
	v_mfma_f32_16x16x32_bf16 v[80:83], v[178:181], v[206:209], v[80:83]
	v_mfma_f32_16x16x32_bf16 v[72:75], v[170:173], v[214:217], v[72:75]
	v_mfma_f32_16x16x32_bf16 v[64:67], v[178:181], v[214:217], v[64:67]
	v_mfma_f32_16x16x32_bf16 v[124:127], v[174:177], v[194:197], v[124:127]
	v_mfma_f32_16x16x32_bf16 v[112:115], v[186:189], v[194:197], v[112:115]
	v_mfma_f32_16x16x32_bf16 v[104:107], v[174:177], v[202:205], v[104:107]
	v_mfma_f32_16x16x32_bf16 v[96:99], v[186:189], v[202:205], v[96:99]
	v_mfma_f32_16x16x32_bf16 v[88:91], v[174:177], v[210:213], v[88:91]
	v_mfma_f32_16x16x32_bf16 v[80:83], v[186:189], v[210:213], v[80:83]
	v_mfma_f32_16x16x32_bf16 v[72:75], v[174:177], v[224:227], v[72:75]
	v_mfma_f32_16x16x32_bf16 v[64:67], v[186:189], v[224:227], v[64:67]
	s_setprio 0
	s_barrier
	s_add_i32 s42, s64, s31
	v_lshl_add_u64 v[148:149], v[148:149], 0, s[36:37]
	s_mov_b32 m0, s42
	ds_read_b128 v[190:193], v155 offset:49152
	ds_read_b128 v[194:197], v155 offset:50176
	ds_read_b128 v[198:201], v155 offset:51200
	ds_read_b128 v[202:205], v155 offset:52224
	ds_read_b128 v[206:209], v155 offset:53248
	ds_read_b128 v[210:213], v155 offset:54272
	ds_read_b128 v[214:217], v155 offset:55296
	ds_read_b128 v[224:227], v155 offset:56320
	global_load_lds_dwordx4 v[148:149], off
	v_lshl_add_u64 v[148:149], v[182:183], 0, s[36:37]
	s_add_i32 m0, s42, 0x2000
	s_add_i32 s42, s65, s31
	global_load_lds_dwordx4 v[148:149], off
	v_lshl_add_u64 v[148:149], v[228:229], 0, s[36:37]
	s_mov_b32 m0, s42
	s_nop 0
	global_load_lds_dwordx4 v[148:149], off
	v_lshl_add_u64 v[148:149], v[230:231], 0, s[36:37]
	s_add_i32 m0, s42, 0x2000
	s_nop 0
	global_load_lds_dwordx4 v[148:149], off
	s_waitcnt vmcnt(6)
	s_waitcnt lgkmcnt(0)
	s_barrier
	s_setprio 1
	s_waitcnt lgkmcnt(0)
	v_mfma_f32_16x16x32_bf16 v[60:63], v[144:147], v[190:193], v[60:63]
	v_mfma_f32_16x16x32_bf16 v[52:55], v[162:165], v[190:193], v[52:55]
	v_mfma_f32_16x16x32_bf16 v[44:47], v[144:147], v[198:201], v[44:47]
	v_mfma_f32_16x16x32_bf16 v[36:39], v[162:165], v[198:201], v[36:39]
	v_mfma_f32_16x16x32_bf16 v[28:31], v[144:147], v[206:209], v[28:31]
	v_mfma_f32_16x16x32_bf16 v[20:23], v[162:165], v[206:209], v[20:23]
	v_mfma_f32_16x16x32_bf16 v[12:15], v[144:147], v[214:217], v[12:15]
	v_mfma_f32_16x16x32_bf16 v[4:7], v[162:165], v[214:217], v[4:7]
	v_mfma_f32_16x16x32_bf16 v[60:63], v[158:161], v[194:197], v[60:63]
	v_mfma_f32_16x16x32_bf16 v[52:55], v[166:169], v[194:197], v[52:55]
	v_mfma_f32_16x16x32_bf16 v[44:47], v[158:161], v[202:205], v[44:47]
	v_mfma_f32_16x16x32_bf16 v[36:39], v[166:169], v[202:205], v[36:39]
	v_mfma_f32_16x16x32_bf16 v[28:31], v[158:161], v[210:213], v[28:31]
	v_mfma_f32_16x16x32_bf16 v[20:23], v[166:169], v[210:213], v[20:23]
	v_mfma_f32_16x16x32_bf16 v[12:15], v[158:161], v[224:227], v[12:15]
	v_mfma_f32_16x16x32_bf16 v[4:7], v[166:169], v[224:227], v[4:7]
	s_setprio 0
	s_setprio 1
	v_mfma_f32_16x16x32_bf16 v[56:59], v[170:173], v[190:193], v[56:59]
	v_mfma_f32_16x16x32_bf16 v[48:51], v[178:181], v[190:193], v[48:51]
	v_mfma_f32_16x16x32_bf16 v[40:43], v[170:173], v[198:201], v[40:43]
	v_mfma_f32_16x16x32_bf16 v[32:35], v[178:181], v[198:201], v[32:35]
	v_mfma_f32_16x16x32_bf16 v[24:27], v[170:173], v[206:209], v[24:27]
	v_mfma_f32_16x16x32_bf16 v[16:19], v[178:181], v[206:209], v[16:19]
	v_mfma_f32_16x16x32_bf16 v[8:11], v[170:173], v[214:217], v[8:11]
	v_mfma_f32_16x16x32_bf16 v[0:3], v[178:181], v[214:217], v[0:3]
	v_mfma_f32_16x16x32_bf16 v[56:59], v[174:177], v[194:197], v[56:59]
	v_mfma_f32_16x16x32_bf16 v[48:51], v[186:189], v[194:197], v[48:51]
	v_mfma_f32_16x16x32_bf16 v[40:43], v[174:177], v[202:205], v[40:43]
	v_mfma_f32_16x16x32_bf16 v[32:35], v[186:189], v[202:205], v[32:35]
	v_mfma_f32_16x16x32_bf16 v[24:27], v[174:177], v[210:213], v[24:27]
	v_mfma_f32_16x16x32_bf16 v[16:19], v[186:189], v[210:213], v[16:19]
	v_mfma_f32_16x16x32_bf16 v[8:11], v[174:177], v[224:227], v[8:11]
	v_mfma_f32_16x16x32_bf16 v[0:3], v[186:189], v[224:227], v[0:3]
	s_setprio 0
	s_barrier
	s_add_u32 s40, s40, 0x100
	s_addc_u32 s41, s41, 0
	s_add_u32 s61, s61, 0x100
	s_addc_u32 s62, s62, 0
	s_cmp_ge_i32 s63, s49
	s_mov_b32 s42, s63
	s_cbranch_scc0 .LBB0_921
	s_branch .LBB0_922
